# v11 + peeled first iteration with three store-aware waits; the new tile's K-step-1 A stage is issued before the epilogue stores
# baseline (speedup 1.0000x reference)
; #define PG8_STAGE(bufoff, gbase, voff) do { _Pragma("unroll") for (int _i = 0; _i < 2; ++_i) \
;         __builtin_amdgcn_global_load_lds((const unsigned*)((const char*)(gbase) + (voff)[_i]), (LAS unsigned*)(lds + (bufoff) + ldsw + _i * 8192), 16, 0, 0); } while (0)
; #define PG8_LDA(dst, b, h) do { _Pragma("unroll") for (int m = 0; m < 4; ++m) _Pragma("unroll") for (int k = 0; k < 2; ++k) dst[m][k] = *(const LAS bf16x8*)(lds + PG8_SA(b, h) + aoff + m * 2048 + k * 1024); } while (0)
; #define PG8_LDB(dst, b, h) do { _Pragma("unroll") for (int n = 0; n < 2; ++n) _Pragma("unroll") for (int k = 0; k < 2; ++k) dst[n][k] = *(const LAS bf16x8*)(lds + PG8_SB(b, h) + boff + n * 2048 + k * 1024); } while (0)
; #define PG8_MMA(ai, bj, At, Bt) do { __builtin_amdgcn_s_setprio(1); _Pragma("unroll") for (int m = 0; m < 4; ++m) _Pragma("unroll") for (int n = 0; n < 2; ++n) _Pragma("unroll") for (int k = 0; k < 2; ++k) \
;         acc[ai][bj][m][n] = __builtin_amdgcn_mfma_f32_16x16x32_bf16(Bt[n][k], At[m][k], acc[ai][bj][m][n], 0, 0, 0); __builtin_amdgcn_s_setprio(0); } while (0)
; #define PG8_WAIT_V(n) asm volatile("s_waitcnt vmcnt(" #n ")" ::: "memory")
; #define PG8_WAIT_L(n) asm volatile("s_waitcnt lgkmcnt(" #n ")" ::: "memory")
; #define PG8_BAR __builtin_amdgcn_s_barrier()
; #define PG8_SCHED __builtin_amdgcn_sched_barrier(0)
; __device__ __forceinline__ void gemm_phase(LAS unsigned char* lds, const GemmP g, const EpiP e) {
;     ...
;         for (int t = 0; t < nt; t += 2) {
;             const bool last = (t == nt - 2);
;             const char* a1 = cA + (size_t)(t + 1) * kstepA;
;             const char* a2 = last ? nA : cA + (size_t)(t + 2) * kstepA; const char* b2 = last ? nB : cB + (size_t)(t + 2) * kstepB;
;             const char* a3 = a2 + kstepA; const char* b3 = b2 + kstepB;
;             PG8_LDB(B0, 0, 0); PG8_LDB(B1, 0, 1); PG8_SCHED; PG8_LDA(At, 0, 0); PG8_STAGE(PG8_SA(1, 1), a1 + hstepA, voffA);
;             PG8_WAIT_V(8); PG8_WAIT_L(0); PG8_BAR; PG8_MMA(0, 0, At, B0); PG8_MMA(0, 1, At, B1); PG8_BAR; PG8_SCHED;
;             PG8_LDA(At, 0, 1); PG8_STAGE(PG8_SB(0, 0), b2, voffB); PG8_STAGE(PG8_SB(0, 1), b2 + hstepB, voffB); PG8_STAGE(PG8_SA(0, 0), a2, voffA);
;             PG8_WAIT_V(8); PG8_WAIT_L(0); PG8_BAR; PG8_MMA(1, 0, At, B0); PG8_MMA(1, 1, At, B1); PG8_BAR; PG8_SCHED;
.LBB0_392:
	s_cmp_lt_i32 s69, 1
	s_cbranch_scc1 .LBB0_395
	s_add_u32 s24, s78, s90
	s_addc_u32 s25, s79, s7
	s_add_i32 s26, s69, -2
	s_add_u32 s27, s40, 0x100
	s_addc_u32 s28, s41, 0
	s_mov_b64 s[18:19], 0
	s_cmp_eq_u32 s99, 0
	s_cbranch_scc1 .LBB0_394
	s_mov_b32 s99, 0
	s_add_u32 s30, s18, 1
	s_addc_u32 s31, s19, 0
	s_add_u32 s16, s18, 2
	s_addc_u32 s17, s19, 0
	s_lshl_b64 s[20:21], s[16:17], s77
	s_add_u32 s19, s78, s20
	s_addc_u32 s20, s79, s21
	s_cmp_eq_u32 s26, s18
	s_cselect_b32 s21, s51, s20
	s_cselect_b32 s20, s50, s19
	s_cselect_b32 s22, s80, s27
	s_cselect_b32 s23, s81, s28
	s_add_u32 s18, s20, s38
	s_addc_u32 s19, s21, s39
	s_add_i32 s29, 0, 0x10000
	v_add_u32_e32 v96, s29, v179
	s_add_i32 s34, 0, 0x14000
	ds_read_b128 v[132:135], v96
	ds_read_b128 v[136:139], v96 offset:1024
	ds_read_b128 v[160:163], v96 offset:2048
	ds_read_b128 v[164:167], v96 offset:3072
	v_add_u32_e32 v96, s34, v179
	ds_read_b128 v[168:171], v96
	ds_read_b128 v[172:175], v96 offset:1024
	ds_read_b128 v[216:219], v96 offset:2048
	ds_read_b128 v[220:223], v96 offset:3072
	s_lshl_b64 s[30:31], s[30:31], s77
	s_add_u32 s30, s24, s30
	s_addc_u32 s31, s25, s31
	v_lshl_add_u64 v[98:99], s[30:31], 0, v[140:141]
	s_add_i32 m0, s92, 0xc000
	ds_read_b128 v[224:227], v188
	ds_read_b128 v[228:231], v188 offset:1024
	ds_read_b128 v[232:235], v188 offset:2048
	ds_read_b128 v[236:239], v188 offset:3072
	ds_read_b128 v[240:243], v188 offset:4096
	ds_read_b128 v[244:247], v188 offset:5120
	ds_read_b128 v[248:251], v188 offset:6144
	ds_read_b128 v[204:207], v188 offset:7168
	s_nop 0
	v_lshl_add_u64 v[98:99], s[30:31], 0, v[142:143]
	s_add_i32 m0, s92, 0xe000
	s_nop 0
	s_nop 0
	s_waitcnt vmcnt(24)
	s_waitcnt lgkmcnt(0)
	s_barrier
	s_setprio 1
	s_waitcnt lgkmcnt(0)
	v_mfma_f32_16x16x32_bf16 v[128:131], v[132:135], v[224:227], v[128:131]
	v_mfma_f32_16x16x32_bf16 v[124:127], v[160:163], v[224:227], v[124:127]
	v_mfma_f32_16x16x32_bf16 v[120:123], v[132:135], v[232:235], v[120:123]
	v_mfma_f32_16x16x32_bf16 v[116:119], v[160:163], v[232:235], v[116:119]
	v_mfma_f32_16x16x32_bf16 v[112:115], v[132:135], v[240:243], v[112:115]
	v_mfma_f32_16x16x32_bf16 v[108:111], v[160:163], v[240:243], v[108:111]
	v_mfma_f32_16x16x32_bf16 v[104:107], v[132:135], v[248:251], v[104:107]
	v_mfma_f32_16x16x32_bf16 v[98:101], v[160:163], v[248:251], v[100:103]
	v_mfma_f32_16x16x32_bf16 v[128:131], v[136:139], v[228:231], v[128:131]
	v_mfma_f32_16x16x32_bf16 v[124:127], v[164:167], v[228:231], v[124:127]
	v_mfma_f32_16x16x32_bf16 v[120:123], v[136:139], v[236:239], v[120:123]
	v_mfma_f32_16x16x32_bf16 v[116:119], v[164:167], v[236:239], v[116:119]
	v_mfma_f32_16x16x32_bf16 v[112:115], v[136:139], v[244:247], v[112:115]
	v_mfma_f32_16x16x32_bf16 v[108:111], v[164:167], v[244:247], v[108:111]
	v_mfma_f32_16x16x32_bf16 v[104:107], v[136:139], v[204:207], v[104:107]
	v_mfma_f32_16x16x32_bf16 v[98:101], v[164:167], v[204:207], v[98:101]
	s_setprio 0
	s_setprio 1
	v_mfma_f32_16x16x32_bf16 v[92:95], v[168:171], v[224:227], v[92:95]
	v_mfma_f32_16x16x32_bf16 v[88:91], v[216:219], v[224:227], v[88:91]
	v_mfma_f32_16x16x32_bf16 v[84:87], v[168:171], v[232:235], v[84:87]
	v_mfma_f32_16x16x32_bf16 v[80:83], v[216:219], v[232:235], v[80:83]
	v_mfma_f32_16x16x32_bf16 v[76:79], v[168:171], v[240:243], v[76:79]
	v_mfma_f32_16x16x32_bf16 v[72:75], v[216:219], v[240:243], v[72:75]
	v_mfma_f32_16x16x32_bf16 v[68:71], v[168:171], v[248:251], v[68:71]
	v_mfma_f32_16x16x32_bf16 v[64:67], v[216:219], v[248:251], v[64:67]
	v_mfma_f32_16x16x32_bf16 v[92:95], v[172:175], v[228:231], v[92:95]
	v_mfma_f32_16x16x32_bf16 v[88:91], v[220:223], v[228:231], v[88:91]
	v_mfma_f32_16x16x32_bf16 v[84:87], v[172:175], v[236:239], v[84:87]
	v_mfma_f32_16x16x32_bf16 v[80:83], v[220:223], v[236:239], v[80:83]
	v_mfma_f32_16x16x32_bf16 v[76:79], v[172:175], v[244:247], v[76:79]
	v_mfma_f32_16x16x32_bf16 v[72:75], v[220:223], v[244:247], v[72:75]
	v_mfma_f32_16x16x32_bf16 v[68:71], v[172:175], v[204:207], v[68:71]
	v_mfma_f32_16x16x32_bf16 v[64:67], v[220:223], v[204:207], v[64:67]
	s_setprio 0
	s_barrier
	s_add_i32 s29, s29, s91
	v_lshl_add_u64 v[176:177], s[22:23], 0, v[146:147]
	s_mov_b32 m0, s29
	ds_read_b128 v[204:207], v188 offset:16384
	ds_read_b128 v[224:227], v188 offset:17408
	ds_read_b128 v[228:231], v188 offset:18432
	ds_read_b128 v[232:235], v188 offset:19456
	ds_read_b128 v[236:239], v188 offset:20480
	ds_read_b128 v[240:243], v188 offset:21504
	ds_read_b128 v[244:247], v188 offset:22528
	ds_read_b128 v[248:251], v188 offset:23552
	global_load_lds_dwordx4 v[176:177], off
	s_add_i32 m0, s29, 0x2000
	v_lshl_add_u64 v[210:211], s[22:23], 0, v[144:145]
	s_add_u32 s22, s22, s48
	s_addc_u32 s23, s23, s49
	s_add_i32 s29, s34, s91
	global_load_lds_dwordx4 v[210:211], off
	v_lshl_add_u64 v[212:213], s[22:23], 0, v[146:147]
	s_mov_b32 m0, s29
	v_lshl_add_u64 v[190:191], s[22:23], 0, v[144:145]
	global_load_lds_dwordx4 v[212:213], off
	s_add_i32 m0, s29, 0x2000
	v_lshl_add_u64 v[102:103], s[20:21], 0, v[140:141]
	global_load_lds_dwordx4 v[190:191], off
	s_mov_b32 m0, s92
	s_nop 0
	global_load_lds_dwordx4 v[102:103], off
	v_lshl_add_u64 v[102:103], s[20:21], 0, v[142:143]
	s_mov_b32 m0, s93
	s_nop 0
	global_load_lds_dwordx4 v[102:103], off
	s_waitcnt vmcnt(24)
	s_waitcnt lgkmcnt(0)
	s_barrier
; #define PG8_STAGE(bufoff, gbase, voff) do { _Pragma("unroll") for (int _i = 0; _i < 2; ++_i) \
;         __builtin_amdgcn_global_load_lds((const unsigned*)((const char*)(gbase) + (voff)[_i]), (LAS unsigned*)(lds + (bufoff) + ldsw + _i * 8192), 16, 0, 0); } while (0)
; #define PG8_LDA(dst, b, h) do { _Pragma("unroll") for (int m = 0; m < 4; ++m) _Pragma("unroll") for (int k = 0; k < 2; ++k) dst[m][k] = *(const LAS bf16x8*)(lds + PG8_SA(b, h) + aoff + m * 2048 + k * 1024); } while (0)
; #define PG8_LDB(dst, b, h) do { _Pragma("unroll") for (int n = 0; n < 2; ++n) _Pragma("unroll") for (int k = 0; k < 2; ++k) dst[n][k] = *(const LAS bf16x8*)(lds + PG8_SB(b, h) + boff + n * 2048 + k * 1024); } while (0)
; #define PG8_MMA(ai, bj, At, Bt) do { __builtin_amdgcn_s_setprio(1); _Pragma("unroll") for (int m = 0; m < 4; ++m) _Pragma("unroll") for (int n = 0; n < 2; ++n) _Pragma("unroll") for (int k = 0; k < 2; ++k) \
;         acc[ai][bj][m][n] = __builtin_amdgcn_mfma_f32_16x16x32_bf16(Bt[n][k], At[m][k], acc[ai][bj][m][n], 0, 0, 0); __builtin_amdgcn_s_setprio(0); } while (0)
; #define PG8_WAIT_V(n) asm volatile("s_waitcnt vmcnt(" #n ")" ::: "memory")
; #define PG8_WAIT_L(n) asm volatile("s_waitcnt lgkmcnt(" #n ")" ::: "memory")
; #define PG8_BAR __builtin_amdgcn_s_barrier()
; #define PG8_SCHED __builtin_amdgcn_sched_barrier(0)
; __device__ __forceinline__ void gemm_phase(LAS unsigned char* lds, const GemmP g, const EpiP e) {
;     ...
;             PG8_WAIT_V(8); PG8_WAIT_L(0); PG8_BAR; PG8_MMA(1, 0, At, B0); PG8_MMA(1, 1, At, B1); PG8_BAR; PG8_SCHED;
;             PG8_LDB(B0, 1, 0); PG8_LDB(B1, 1, 1); PG8_SCHED; PG8_LDA(At, 1, 0); PG8_STAGE(PG8_SA(0, 1), a2 + hstepA, voffA);
;             PG8_WAIT_V(8); PG8_WAIT_L(0); PG8_BAR; PG8_MMA(0, 0, At, B0); PG8_MMA(0, 1, At, B1); PG8_BAR; PG8_SCHED;
	s_setprio 1
	s_waitcnt lgkmcnt(0)
	v_mfma_f32_16x16x32_bf16 v[60:63], v[132:135], v[204:207], v[60:63]
	v_mfma_f32_16x16x32_bf16 v[56:59], v[160:163], v[204:207], v[56:59]
	v_mfma_f32_16x16x32_bf16 v[52:55], v[132:135], v[228:231], v[52:55]
	v_mfma_f32_16x16x32_bf16 v[48:51], v[160:163], v[228:231], v[48:51]
	v_mfma_f32_16x16x32_bf16 v[44:47], v[132:135], v[236:239], v[44:47]
	v_mfma_f32_16x16x32_bf16 v[40:43], v[160:163], v[236:239], v[40:43]
	v_mfma_f32_16x16x32_bf16 v[36:39], v[132:135], v[244:247], v[36:39]
	v_mfma_f32_16x16x32_bf16 v[32:35], v[160:163], v[244:247], v[32:35]
	v_mfma_f32_16x16x32_bf16 v[60:63], v[136:139], v[224:227], v[60:63]
	v_mfma_f32_16x16x32_bf16 v[56:59], v[164:167], v[224:227], v[56:59]
	v_mfma_f32_16x16x32_bf16 v[52:55], v[136:139], v[232:235], v[52:55]
	v_mfma_f32_16x16x32_bf16 v[48:51], v[164:167], v[232:235], v[48:51]
	v_mfma_f32_16x16x32_bf16 v[44:47], v[136:139], v[240:243], v[44:47]
	v_mfma_f32_16x16x32_bf16 v[40:43], v[164:167], v[240:243], v[40:43]
	v_mfma_f32_16x16x32_bf16 v[36:39], v[136:139], v[248:251], v[36:39]
	v_mfma_f32_16x16x32_bf16 v[32:35], v[164:167], v[248:251], v[32:35]
	s_setprio 0
	s_setprio 1
	v_mfma_f32_16x16x32_bf16 v[28:31], v[168:171], v[204:207], v[28:31]
	v_mfma_f32_16x16x32_bf16 v[24:27], v[216:219], v[204:207], v[24:27]
	v_mfma_f32_16x16x32_bf16 v[20:23], v[168:171], v[228:231], v[20:23]
	v_mfma_f32_16x16x32_bf16 v[16:19], v[216:219], v[228:231], v[16:19]
	v_mfma_f32_16x16x32_bf16 v[12:15], v[168:171], v[236:239], v[12:15]
	v_mfma_f32_16x16x32_bf16 v[8:11], v[216:219], v[236:239], v[8:11]
	v_mfma_f32_16x16x32_bf16 v[4:7], v[168:171], v[244:247], v[4:7]
	v_mfma_f32_16x16x32_bf16 v[0:3], v[216:219], v[244:247], v[0:3]
	v_mfma_f32_16x16x32_bf16 v[28:31], v[172:175], v[224:227], v[28:31]
	v_mfma_f32_16x16x32_bf16 v[24:27], v[220:223], v[224:227], v[24:27]
	v_mfma_f32_16x16x32_bf16 v[20:23], v[172:175], v[232:235], v[20:23]
	v_mfma_f32_16x16x32_bf16 v[16:19], v[220:223], v[232:235], v[16:19]
	v_mfma_f32_16x16x32_bf16 v[12:15], v[172:175], v[240:243], v[12:15]
	v_mfma_f32_16x16x32_bf16 v[8:11], v[220:223], v[240:243], v[8:11]
	v_mfma_f32_16x16x32_bf16 v[4:7], v[172:175], v[248:251], v[4:7]
	v_mfma_f32_16x16x32_bf16 v[0:3], v[220:223], v[248:251], v[0:3]
	s_setprio 0
	s_barrier
	s_add_i32 s22, 0, 0x18000
	v_add_u32_e32 v96, s22, v179
	s_add_i32 s23, 0, 0x1c000
	ds_read_b128 v[132:135], v96
	ds_read_b128 v[136:139], v96 offset:1024
	ds_read_b128 v[160:163], v96 offset:2048
	ds_read_b128 v[164:167], v96 offset:3072
	v_add_u32_e32 v96, s23, v179
	ds_read_b128 v[168:171], v96
	ds_read_b128 v[172:175], v96 offset:1024
	ds_read_b128 v[204:207], v96 offset:2048
	ds_read_b128 v[216:219], v96 offset:3072
	s_add_u32 s20, s20, s90
	s_addc_u32 s21, s21, s7
	s_mov_b32 m0, s73
	v_lshl_add_u64 v[102:103], s[20:21], 0, v[140:141]
	ds_read_b128 v[220:223], v188 offset:32768
	ds_read_b128 v[224:227], v188 offset:33792
	ds_read_b128 v[228:231], v188 offset:34816
	ds_read_b128 v[232:235], v188 offset:35840
	ds_read_b128 v[236:239], v188 offset:36864
	ds_read_b128 v[240:243], v188 offset:37888
	ds_read_b128 v[244:247], v188 offset:38912
	ds_read_b128 v[248:251], v188 offset:39936
	global_load_lds_dwordx4 v[102:103], off
	v_lshl_add_u64 v[102:103], s[20:21], 0, v[142:143]
	s_mov_b32 m0, s4
	s_nop 0
	global_load_lds_dwordx4 v[102:103], off
	s_waitcnt vmcnt(24)
	s_waitcnt lgkmcnt(0)
	s_barrier
	s_setprio 1
	s_waitcnt lgkmcnt(0)
	v_mfma_f32_16x16x32_bf16 v[128:131], v[132:135], v[220:223], v[128:131]
	v_mfma_f32_16x16x32_bf16 v[124:127], v[160:163], v[220:223], v[124:127]
	v_mfma_f32_16x16x32_bf16 v[120:123], v[132:135], v[228:231], v[120:123]
	v_mfma_f32_16x16x32_bf16 v[116:119], v[160:163], v[228:231], v[116:119]
	v_mfma_f32_16x16x32_bf16 v[112:115], v[132:135], v[236:239], v[112:115]
	v_mfma_f32_16x16x32_bf16 v[108:111], v[160:163], v[236:239], v[108:111]
	v_mfma_f32_16x16x32_bf16 v[102:105], v[132:135], v[244:247], v[104:107]
	v_mfma_f32_16x16x32_bf16 v[98:101], v[160:163], v[244:247], v[98:101]
	v_mfma_f32_16x16x32_bf16 v[128:131], v[136:139], v[224:227], v[128:131]
	v_mfma_f32_16x16x32_bf16 v[124:127], v[164:167], v[224:227], v[124:127]
	v_mfma_f32_16x16x32_bf16 v[120:123], v[136:139], v[232:235], v[120:123]
	v_mfma_f32_16x16x32_bf16 v[116:119], v[164:167], v[232:235], v[116:119]
	v_mfma_f32_16x16x32_bf16 v[112:115], v[136:139], v[240:243], v[112:115]
	v_mfma_f32_16x16x32_bf16 v[108:111], v[164:167], v[240:243], v[108:111]
	v_mfma_f32_16x16x32_bf16 v[104:107], v[136:139], v[248:251], v[102:105]
	v_mfma_f32_16x16x32_bf16 v[100:103], v[164:167], v[248:251], v[98:101]
	s_setprio 0
	s_setprio 1
	v_mfma_f32_16x16x32_bf16 v[92:95], v[168:171], v[220:223], v[92:95]
	v_mfma_f32_16x16x32_bf16 v[88:91], v[204:207], v[220:223], v[88:91]
	v_mfma_f32_16x16x32_bf16 v[84:87], v[168:171], v[228:231], v[84:87]
	v_mfma_f32_16x16x32_bf16 v[80:83], v[204:207], v[228:231], v[80:83]
	v_mfma_f32_16x16x32_bf16 v[76:79], v[168:171], v[236:239], v[76:79]
	v_mfma_f32_16x16x32_bf16 v[72:75], v[204:207], v[236:239], v[72:75]
	v_mfma_f32_16x16x32_bf16 v[68:71], v[168:171], v[244:247], v[68:71]
	v_mfma_f32_16x16x32_bf16 v[64:67], v[204:207], v[244:247], v[64:67]
	v_mfma_f32_16x16x32_bf16 v[92:95], v[172:175], v[224:227], v[92:95]
	v_mfma_f32_16x16x32_bf16 v[88:91], v[216:219], v[224:227], v[88:91]
	v_mfma_f32_16x16x32_bf16 v[84:87], v[172:175], v[232:235], v[84:87]
	v_mfma_f32_16x16x32_bf16 v[80:83], v[216:219], v[232:235], v[80:83]
	v_mfma_f32_16x16x32_bf16 v[76:79], v[172:175], v[240:243], v[76:79]
	v_mfma_f32_16x16x32_bf16 v[72:75], v[216:219], v[240:243], v[72:75]
	v_mfma_f32_16x16x32_bf16 v[68:71], v[172:175], v[248:251], v[68:71]
	v_mfma_f32_16x16x32_bf16 v[64:67], v[216:219], v[248:251], v[64:67]
	s_setprio 0
	s_barrier
; #define PG8_STAGE(bufoff, gbase, voff) do { _Pragma("unroll") for (int _i = 0; _i < 2; ++_i) \
;         __builtin_amdgcn_global_load_lds((const unsigned*)((const char*)(gbase) + (voff)[_i]), (LAS unsigned*)(lds + (bufoff) + ldsw + _i * 8192), 16, 0, 0); } while (0)
; #define PG8_LDA(dst, b, h) do { _Pragma("unroll") for (int m = 0; m < 4; ++m) _Pragma("unroll") for (int k = 0; k < 2; ++k) dst[m][k] = *(const LAS bf16x8*)(lds + PG8_SA(b, h) + aoff + m * 2048 + k * 1024); } while (0)
; #define PG8_MMA(ai, bj, At, Bt) do { __builtin_amdgcn_s_setprio(1); _Pragma("unroll") for (int m = 0; m < 4; ++m) _Pragma("unroll") for (int n = 0; n < 2; ++n) _Pragma("unroll") for (int k = 0; k < 2; ++k) \
;         acc[ai][bj][m][n] = __builtin_amdgcn_mfma_f32_16x16x32_bf16(Bt[n][k], At[m][k], acc[ai][bj][m][n], 0, 0, 0); __builtin_amdgcn_s_setprio(0); } while (0)
; #define PG8_WAIT_V(n) asm volatile("s_waitcnt vmcnt(" #n ")" ::: "memory")
; #define PG8_WAIT_L(n) asm volatile("s_waitcnt lgkmcnt(" #n ")" ::: "memory")
; #define PG8_BAR __builtin_amdgcn_s_barrier()
; #define PG8_SCHED __builtin_amdgcn_sched_barrier(0)
; __device__ __forceinline__ void gemm_phase(LAS unsigned char* lds, const GemmP g, const EpiP e) {
;     ...
;             PG8_LDA(At, 1, 1); PG8_STAGE(PG8_SB(1, 0), b3, voffB); PG8_STAGE(PG8_SB(1, 1), b3 + hstepB, voffB); PG8_STAGE(PG8_SA(1, 0), a3, voffA);
;             PG8_WAIT_V(8); PG8_WAIT_L(0); PG8_BAR; PG8_MMA(1, 0, At, B0); PG8_MMA(1, 1, At, B1); PG8_BAR; PG8_SCHED;
;         }
	s_add_i32 s20, s22, s91
	v_lshl_add_u64 v[98:99], v[176:177], 0, s[96:97]
	s_mov_b32 m0, s20
	ds_read_b128 v[220:223], v188 offset:49152
	ds_read_b128 v[224:227], v188 offset:50176
	ds_read_b128 v[228:231], v188 offset:51200
	ds_read_b128 v[232:235], v188 offset:52224
	ds_read_b128 v[236:239], v188 offset:53248
	ds_read_b128 v[240:243], v188 offset:54272
	ds_read_b128 v[244:247], v188 offset:55296
	ds_read_b128 v[248:251], v188 offset:56320
	global_load_lds_dwordx4 v[98:99], off
	v_lshl_add_u64 v[98:99], v[210:211], 0, s[96:97]
	s_add_i32 m0, s20, 0x2000
	s_add_i32 s20, s23, s91
	global_load_lds_dwordx4 v[98:99], off
	v_lshl_add_u64 v[98:99], v[212:213], 0, s[96:97]
	s_mov_b32 m0, s20
	s_nop 0
	global_load_lds_dwordx4 v[98:99], off
	v_lshl_add_u64 v[98:99], v[190:191], 0, s[96:97]
	s_add_i32 m0, s20, 0x2000
	s_nop 0
	global_load_lds_dwordx4 v[98:99], off
	v_lshl_add_u64 v[98:99], s[18:19], 0, v[140:141]
	s_mov_b32 m0, s5
	s_nop 0
	global_load_lds_dwordx4 v[98:99], off
	v_lshl_add_u64 v[98:99], s[18:19], 0, v[142:143]
	s_mov_b32 m0, s44
	s_nop 0
	global_load_lds_dwordx4 v[98:99], off
	s_waitcnt vmcnt(8)
	s_waitcnt lgkmcnt(0)
	s_barrier
	s_setprio 1
	s_waitcnt lgkmcnt(0)
	v_mfma_f32_16x16x32_bf16 v[60:63], v[132:135], v[220:223], v[60:63]
	v_mfma_f32_16x16x32_bf16 v[56:59], v[160:163], v[220:223], v[56:59]
	v_mfma_f32_16x16x32_bf16 v[52:55], v[132:135], v[228:231], v[52:55]
	v_mfma_f32_16x16x32_bf16 v[48:51], v[160:163], v[228:231], v[48:51]
	v_mfma_f32_16x16x32_bf16 v[44:47], v[132:135], v[236:239], v[44:47]
	v_mfma_f32_16x16x32_bf16 v[40:43], v[160:163], v[236:239], v[40:43]
	v_mfma_f32_16x16x32_bf16 v[36:39], v[132:135], v[244:247], v[36:39]
	v_mfma_f32_16x16x32_bf16 v[32:35], v[160:163], v[244:247], v[32:35]
	v_mfma_f32_16x16x32_bf16 v[60:63], v[136:139], v[224:227], v[60:63]
	v_mfma_f32_16x16x32_bf16 v[56:59], v[164:167], v[224:227], v[56:59]
	v_mfma_f32_16x16x32_bf16 v[52:55], v[136:139], v[232:235], v[52:55]
	v_mfma_f32_16x16x32_bf16 v[48:51], v[164:167], v[232:235], v[48:51]
	v_mfma_f32_16x16x32_bf16 v[44:47], v[136:139], v[240:243], v[44:47]
	v_mfma_f32_16x16x32_bf16 v[40:43], v[164:167], v[240:243], v[40:43]
	v_mfma_f32_16x16x32_bf16 v[36:39], v[136:139], v[248:251], v[36:39]
	v_mfma_f32_16x16x32_bf16 v[32:35], v[164:167], v[248:251], v[32:35]
	s_setprio 0
	s_setprio 1
	v_mfma_f32_16x16x32_bf16 v[28:31], v[168:171], v[220:223], v[28:31]
	v_mfma_f32_16x16x32_bf16 v[24:27], v[204:207], v[220:223], v[24:27]
	v_mfma_f32_16x16x32_bf16 v[20:23], v[168:171], v[228:231], v[20:23]
	v_mfma_f32_16x16x32_bf16 v[16:19], v[204:207], v[228:231], v[16:19]
	v_mfma_f32_16x16x32_bf16 v[12:15], v[168:171], v[236:239], v[12:15]
	v_mfma_f32_16x16x32_bf16 v[8:11], v[204:207], v[236:239], v[8:11]
	v_mfma_f32_16x16x32_bf16 v[4:7], v[168:171], v[244:247], v[4:7]
	v_mfma_f32_16x16x32_bf16 v[0:3], v[204:207], v[244:247], v[0:3]
	v_mfma_f32_16x16x32_bf16 v[28:31], v[172:175], v[224:227], v[28:31]
	v_mfma_f32_16x16x32_bf16 v[24:27], v[216:219], v[224:227], v[24:27]
	v_mfma_f32_16x16x32_bf16 v[20:23], v[172:175], v[232:235], v[20:23]
	v_mfma_f32_16x16x32_bf16 v[16:19], v[216:219], v[232:235], v[16:19]
	v_mfma_f32_16x16x32_bf16 v[12:15], v[172:175], v[240:243], v[12:15]
	v_mfma_f32_16x16x32_bf16 v[8:11], v[216:219], v[240:243], v[8:11]
	v_mfma_f32_16x16x32_bf16 v[4:7], v[172:175], v[248:251], v[4:7]
	v_mfma_f32_16x16x32_bf16 v[0:3], v[216:219], v[248:251], v[0:3]
	s_setprio 0
	s_barrier
	s_add_u32 s27, s27, 0x100
	s_addc_u32 s28, s28, 0
	s_cmp_ge_i32 s16, s69
	s_mov_b64 s[18:19], s[16:17]
	s_cbranch_scc0 .LBB0_394
	s_branch .LBB0_395

; #define PG8_STAGE(bufoff, gbase, voff) do { _Pragma("unroll") for (int _i = 0; _i < 2; ++_i) \
;         __builtin_amdgcn_global_load_lds((const unsigned*)((const char*)(gbase) + (voff)[_i]), (LAS unsigned*)(lds + (bufoff) + ldsw + _i * 8192), 16, 0, 0); } while (0)
; #define PG8_LDA(dst, b, h) do { _Pragma("unroll") for (int m = 0; m < 4; ++m) _Pragma("unroll") for (int k = 0; k < 2; ++k) dst[m][k] = *(const LAS bf16x8*)(lds + PG8_SA(b, h) + aoff + m * 2048 + k * 1024); } while (0)
; #define PG8_LDB(dst, b, h) do { _Pragma("unroll") for (int n = 0; n < 2; ++n) _Pragma("unroll") for (int k = 0; k < 2; ++k) dst[n][k] = *(const LAS bf16x8*)(lds + PG8_SB(b, h) + boff + n * 2048 + k * 1024); } while (0)
; #define PG8_SCHED __builtin_amdgcn_sched_barrier(0)
; __device__ __forceinline__ void gemm_phase(LAS unsigned char* lds, const GemmP g, const EpiP e) {
;     ...
;             const char* a2 = last ? nA : cA + (size_t)(t + 2) * kstepA; const char* b2 = last ? nB : cB + (size_t)(t + 2) * kstepB;
;             const char* a3 = a2 + kstepA; const char* b3 = b2 + kstepB;
;             PG8_LDB(B0, 0, 0); PG8_LDB(B1, 0, 1); PG8_SCHED; PG8_LDA(At, 0, 0); PG8_STAGE(PG8_SA(1, 1), a1 + hstepA, voffA);
;     ...
;         cur = nxt; cA = nA; cB = nB; ++ui;
.LBB0_395:
	s_and_b64 vcc, exec, s[14:15]
	s_cbranch_vccnz .Lce_skip
	s_add_u32 s30, s50, s90
	s_addc_u32 s31, s51, s7
	s_add_u32 s30, s30, s38
	s_addc_u32 s31, s31, s39
	v_lshl_add_u64 v[98:99], s[30:31], 0, v[140:141]
	s_add_i32 m0, s92, 0xc000
	s_nop 0
	global_load_lds_dwordx4 v[98:99], off
	v_lshl_add_u64 v[98:99], s[30:31], 0, v[142:143]
	s_add_i32 m0, s92, 0xe000
	s_nop 0
	global_load_lds_dwordx4 v[98:99], off
